# v59 + grid barrier: XCD leader bumps the XCD generation word before its own buffer_inv (12 of 13 instances)
# baseline (speedup 1.0000x reference)
; __device__ __forceinline__ unsigned xb_ld(unsigned* p)              { return __hip_atomic_load(p, __ATOMIC_RELAXED, __HIP_MEMORY_SCOPE_AGENT); }
; __device__ __forceinline__ unsigned xb_add(unsigned* p, unsigned v) { return __hip_atomic_fetch_add(p, v, __ATOMIC_RELAXED, __HIP_MEMORY_SCOPE_AGENT); }
; #define XB_SPIN(cond, bar) do { unsigned _sp = 0; while (cond) { __builtin_amdgcn_s_sleep(1); \
;     if ((++_sp & 255u) == 0u) { if (xb_ld(&(bar)[XB_TMO])) break; if (_sp > XB_SPIN_CAP) { atomicAdd(&(bar)[XB_TMO], 1u); break; } } } } while (0)
; __device__ __forceinline__ void xcd_barrier(const XcdBarrier& b) {
;     ...
;             const unsigned og = xb_add(&bar[XB_TOP], 1u);
;             const unsigned tg = og / nx;
;             if (og + 1u == (tg + 1u) * nx) xb_add(&bar[XB_TOPGEN], 1u);
;             else XB_SPIN(xb_ld(&bar[XB_TOPGEN]) == tg, bar);
;             __builtin_amdgcn_fence(__ATOMIC_ACQUIRE, "agent");
;             xb_add(&bar[XB_XGEN(b.x)], 1u);
;             asm volatile("s_waitcnt vmcnt(0)" ::: "memory");
.LBB0_321:
	s_or_b64 exec, exec, s[10:11]
	s_mov_b64 s[10:11], exec
	v_mbcnt_lo_u32_b32 v1, s10, 0
	v_mbcnt_hi_u32_b32 v1, s11, v1
	v_cmp_eq_u32_e32 vcc, 0, v1
	s_waitcnt vmcnt(0)
	s_and_saveexec_b64 s[12:13], vcc
	s_cbranch_execz .LBB0_323
	s_bcnt1_i32_b64 s10, s[10:11]
	v_mov_b32_e32 v1, 0x2000
	v_mov_b32_e32 v2, s10
	global_atomic_add v1, v2, s[8:9] offset:1024
.LBB0_323:
	s_or_b64 exec, exec, s[12:13]
	buffer_inv sc1
	s_waitcnt vmcnt(0)

; __device__ __forceinline__ unsigned xb_ld(unsigned* p)              { return __hip_atomic_load(p, __ATOMIC_RELAXED, __HIP_MEMORY_SCOPE_AGENT); }
; __device__ __forceinline__ unsigned xb_add(unsigned* p, unsigned v) { return __hip_atomic_fetch_add(p, v, __ATOMIC_RELAXED, __HIP_MEMORY_SCOPE_AGENT); }
; #define XB_SPIN(cond, bar) do { unsigned _sp = 0; while (cond) { __builtin_amdgcn_s_sleep(1); \
;     if ((++_sp & 255u) == 0u) { if (xb_ld(&(bar)[XB_TMO])) break; if (_sp > XB_SPIN_CAP) { atomicAdd(&(bar)[XB_TMO], 1u); break; } } } } while (0)
; __device__ __forceinline__ void xcd_barrier(const XcdBarrier& b) {
;     ...
;             const unsigned og = xb_add(&bar[XB_TOP], 1u);
;             const unsigned tg = og / nx;
;             if (og + 1u == (tg + 1u) * nx) xb_add(&bar[XB_TOPGEN], 1u);
;             else XB_SPIN(xb_ld(&bar[XB_TOPGEN]) == tg, bar);
;             __builtin_amdgcn_fence(__ATOMIC_ACQUIRE, "agent");
;             xb_add(&bar[XB_XGEN(b.x)], 1u);
;             asm volatile("s_waitcnt vmcnt(0)" ::: "memory");
.LBB0_444:
	s_or_b64 exec, exec, s[8:9]
	s_mov_b64 s[8:9], exec
	v_mbcnt_lo_u32_b32 v1, s8, 0
	v_mbcnt_hi_u32_b32 v1, s9, v1
	v_cmp_eq_u32_e32 vcc, 0, v1
	s_waitcnt vmcnt(0)
	s_and_saveexec_b64 s[10:11], vcc
	s_cbranch_execz .LBB0_446
	s_bcnt1_i32_b64 s8, s[8:9]
	v_mov_b32_e32 v1, 0x2000
	v_mov_b32_e32 v2, s8
	global_atomic_add v1, v2, s[6:7] offset:1024
.LBB0_446:
	s_or_b64 exec, exec, s[10:11]
	buffer_inv sc1
	s_waitcnt vmcnt(0)

; __device__ __forceinline__ unsigned xb_ld(unsigned* p)              { return __hip_atomic_load(p, __ATOMIC_RELAXED, __HIP_MEMORY_SCOPE_AGENT); }
; __device__ __forceinline__ unsigned xb_add(unsigned* p, unsigned v) { return __hip_atomic_fetch_add(p, v, __ATOMIC_RELAXED, __HIP_MEMORY_SCOPE_AGENT); }
; #define XB_SPIN(cond, bar) do { unsigned _sp = 0; while (cond) { __builtin_amdgcn_s_sleep(1); \
;     if ((++_sp & 255u) == 0u) { if (xb_ld(&(bar)[XB_TMO])) break; if (_sp > XB_SPIN_CAP) { atomicAdd(&(bar)[XB_TMO], 1u); break; } } } } while (0)
; __device__ __forceinline__ void xcd_barrier(const XcdBarrier& b) {
;     ...
;             const unsigned og = xb_add(&bar[XB_TOP], 1u);
;             const unsigned tg = og / nx;
;             if (og + 1u == (tg + 1u) * nx) xb_add(&bar[XB_TOPGEN], 1u);
;             else XB_SPIN(xb_ld(&bar[XB_TOPGEN]) == tg, bar);
;             __builtin_amdgcn_fence(__ATOMIC_ACQUIRE, "agent");
;             xb_add(&bar[XB_XGEN(b.x)], 1u);
;             asm volatile("s_waitcnt vmcnt(0)" ::: "memory");
.LBB0_607:
	s_or_b64 exec, exec, s[10:11]
	s_mov_b64 s[10:11], exec
	v_mbcnt_lo_u32_b32 v1, s10, 0
	v_mbcnt_hi_u32_b32 v1, s11, v1
	v_cmp_eq_u32_e32 vcc, 0, v1
	s_waitcnt vmcnt(0)
	s_and_saveexec_b64 s[12:13], vcc
	s_cbranch_execz .LBB0_609
	s_bcnt1_i32_b64 s5, s[10:11]
	v_readlane_b32 s10, v254, 13
	v_mov_b32_e32 v1, s5
	v_readlane_b32 s11, v254, 14
	s_nop 4
	global_atomic_add v203, v1, s[10:11]
